# rope-phase meta key/value tasks: the three later loads of a task hoisted next to the first two (one memory round trip per task instead of four)
# baseline (speedup 1.0000x reference)
.LBB0_952:
	s_or_b64 exec, exec, s[18:19]
	s_waitcnt lgkmcnt(0)
	v_lshl_add_u64 v[18:19], v[4:5], 2, s[8:9]
	v_or_b32_e32 v21, s27, v0
	v_lshlrev_b32_e32 v148, 7, v21
	s_lshl_b64 s[14:15], s[16:17], 1
	s_and_b32 s17, s26, 0x100
	v_lshl_add_u64 v[4:5], v[4:5], 1, s[12:13]
	s_waitcnt vmcnt(0)
	v_cvt_pk_bf16_f32 v20, v152, s0
	v_lshl_add_u64 v[18:19], s[10:11], 0, v[148:149]
	v_lshl_add_u64 v[18:19], v[18:19], 0, s[14:15]
	global_store_short v[18:19], v20, off
	v_add_u32_e32 v18, s17, v17
	s_and_b32 s17, s25, 0x60
	v_or3_b32 v18, v18, s17, v1
	s_mul_hi_i32 s17, s16, 0x4400
	s_mulk_i32 s16, 0x4400
	s_add_u32 s16, s23, s16
	s_addc_u32 s17, s24, s17
	v_lshlrev_b32_e32 v18, 2, v18
	s_lshl_b32 s18, s27, 2
	s_add_u32 s16, s16, s18
	s_addc_u32 s17, s17, 0
	v_lshlrev_b32_e32 v148, 2, v0
	s_add_i32 s20, s20, s84
	s_add_i32 s26, s26, s96
	s_waitcnt vmcnt(0)
	v_mul_f32_e32 v19, v154, v154
	ds_bpermute_b32 v19, v9, v19
	s_waitcnt lgkmcnt(0)
	v_fmac_f32_e32 v19, v154, v154
	ds_bpermute_b32 v20, v10, v19
	s_waitcnt lgkmcnt(0)
	v_add_f32_e32 v19, v19, v20
	ds_bpermute_b32 v20, v11, v19
	s_waitcnt lgkmcnt(0)
	v_add_f32_e32 v19, v19, v20
	ds_bpermute_b32 v20, v12, v19
	s_waitcnt lgkmcnt(0)
	v_add_f32_e32 v19, v19, v20
	ds_bpermute_b32 v20, v13, v19
	s_waitcnt lgkmcnt(0)
	v_add_f32_e32 v19, v19, v20
	ds_bpermute_b32 v20, v14, v19
	s_waitcnt lgkmcnt(0)
	v_add_f32_e32 v19, v19, v20
	v_fmamk_f32 v19, v19, 0x3c800000, v207
	v_rsq_f32_e32 v19, v19
	s_nop 0
	v_mul_f32_e32 v18, v154, v19
	v_mul_f32_e32 v18, v7, v18
	v_cvt_pk_bf16_f32 v18, v18, s0
	global_store_short v[4:5], v18, off
	v_lshl_add_u64 v[4:5], s[16:17], 0, v[148:149]
	v_add_co_u32_e32 v4, vcc, s33, v4
	v_lshlrev_b32_e32 v148, 5, v21
	s_nop 0
	v_addc_co_u32_e32 v5, vcc, 0, v5, vcc
	s_waitcnt vmcnt(0)
	v_cvt_pk_bf16_f32 v18, v158, s0
	v_lshl_add_u64 v[4:5], s[4:5], 0, v[148:149]
	v_lshl_add_u64 v[4:5], v[4:5], 0, s[14:15]
	v_readlane_b32 s14, v253, 54
	s_add_i32 s25, s25, s14
	s_cmpk_gt_i32 s20, 0x7f
	global_store_short v[4:5], v18, off
	s_cbranch_scc1 .LBB0_957

.LBB0_955:
	s_or_b64 exec, exec, s[14:15]
	v_lshlrev_b32_e32 v150, 2, v4
	global_load_dword v152, v150, s[8:9]
	s_mul_hi_i32 s99, s16, 0x4400
	s_mul_i32 s98, s16, 0x4400
	s_add_u32 s98, s23, s98
	s_addc_u32 s99, s24, s99
	s_and_b32 s100, s26, 0x100
	v_add_u32_e32 v153, s100, v17
	s_and_b32 s100, s25, 0x60
	v_or3_b32 v153, v153, s100, v1
	v_lshlrev_b32_e32 v153, 2, v153
	global_load_dword v154, v153, s[98:99]
	s_lshl_b32 s100, s27, 2
	s_add_u32 s100, s98, s100
	s_addc_u32 s101, s99, 0
	s_add_u32 s100, s100, s33
	s_addc_u32 s101, s101, 0
	v_lshlrev_b32_e32 v156, 2, v0
	global_load_dword v158, v156, s[100:101] offset:3072
	s_waitcnt vmcnt(0)
	v_mul_f32_e32 v20, v18, v18
	v_fmac_f32_e32 v20, v19, v19
	ds_bpermute_b32 v21, v9, v20
	s_lshl_b32 s15, s16, 1
	s_and_b32 s14, s16, -13
	s_lshr_b32 s18, s16, 1
	s_and_b32 s15, s15, 8
	s_waitcnt lgkmcnt(0)
	v_add_f32_e32 v20, v20, v21
	ds_bpermute_b32 v21, v10, v20
	s_and_b32 s18, s18, 4
	s_or_b32 s14, s15, s14
	s_or_b32 s30, s14, s18
	s_lshr_b32 s18, s30, 2
	s_waitcnt lgkmcnt(0)
	v_add_f32_e32 v20, v20, v21
	ds_bpermute_b32 v21, v11, v20
	s_ashr_i32 s14, s30, 31
	s_add_u32 s15, s30, s27
	s_addc_u32 s14, s14, 0
	s_mul_hi_u32 s19, s15, 0xc0
	s_waitcnt lgkmcnt(0)
	v_add_f32_e32 v20, v20, v21
	ds_bpermute_b32 v21, v12, v20
	s_mulk_i32 s14, 0xc0
	s_mulk_i32 s15, 0xc0
	s_add_i32 s19, s19, s14
	s_add_u32 s14, s21, s15
	s_waitcnt lgkmcnt(0)
	v_add_f32_e32 v20, v20, v21
	ds_bpermute_b32 v21, v13, v20
	s_addc_u32 s15, s22, s19
	s_waitcnt lgkmcnt(0)
	v_add_f32_e32 v20, v20, v21
	ds_bpermute_b32 v21, v14, v20
	s_waitcnt lgkmcnt(0)
	v_add_f32_e32 v20, v20, v21
	v_fmamk_f32 v20, v20, 0x3c2aaaab, v207
	v_rsq_f32_e32 v20, v20
	v_bitop3_b32 v21, s18, v30, 3 bitop3:0x6c
	v_lshl_or_b32 v21, v21, 4, v31
	v_mul_f32_e32 v18, v18, v20
	v_mul_f32_e32 v19, v19, v20
	v_mul_f32_e32 v18, v8, v18
	v_mul_f32_e32 v20, v6, v19
	ds_bpermute_b32 v19, v13, v18
	v_cvt_pk_bf16_f32 v20, v20, s0
	global_store_short v21, v20, s[14:15]
	s_and_saveexec_b64 s[18:19], s[0:1]
	s_cbranch_execz .LBB0_952
	v_cvt_f32_i32_e32 v20, s16
	s_bfe_u32 s30, s30, 0x20002
	v_mul_f32_e32 v20, v15, v20
	v_cvt_f64_f32_e32 v[20:21], v20
	v_mul_f64 v[22:23], v[20:21], s[38:39]
	v_rndne_f64_e32 v[22:23], v[22:23]
	v_fma_f64 v[20:21], v[20:21], s[38:39], -v[22:23]
	v_cvt_f32_f64_e32 v20, v[20:21]
	v_sin_f32_e32 v21, v20
	v_cos_f32_e32 v20, v20
	v_xor_b32_e32 v22, s30, v16
	s_waitcnt lgkmcnt(0)
	v_mul_f32_e32 v19, v21, v19
	v_cndmask_b32_e64 v19, v19, -v19, s[2:3]
	v_fmac_f32_e32 v19, v20, v18
	v_cvt_pk_bf16_f32 v18, v19, s0
	v_lshl_or_b32 v19, v22, 4, v31
	global_store_short v19, v18, s[14:15]
	s_branch .LBB0_952
